# GEMM unit heads: accumulator zero-initialisation issued as 64 two-register moves instead of 128 single moves
# speedup vs baseline: 1.0099x; 1.0083x over previous
.LBB0_212:
	v_lshl_add_u64 v[140:141], v[4:5], 0, s[74:75]
	v_mov_b64_e32 v[4:5], 0
	v_lshl_add_u64 v[142:143], v[6:7], 0, s[72:73]
	s_mov_b32 s7, -2
	v_mov_b64_e32 v[6:7], 0
	v_mov_b64_e32 v[8:9], 0
	v_mov_b64_e32 v[10:11], 0
	v_mov_b64_e32 v[20:21], 0
	v_mov_b64_e32 v[22:23], 0
	v_mov_b64_e32 v[24:25], 0
	v_mov_b64_e32 v[26:27], 0
	v_mov_b64_e32 v[36:37], 0
	v_mov_b64_e32 v[38:39], 0
	v_mov_b64_e32 v[40:41], 0
	v_mov_b64_e32 v[42:43], 0
	v_mov_b64_e32 v[52:53], 0
	v_mov_b64_e32 v[54:55], 0
	v_mov_b64_e32 v[56:57], 0
	v_mov_b64_e32 v[58:59], 0
	v_mov_b64_e32 v[12:13], 0
	v_mov_b64_e32 v[14:15], 0
	v_mov_b64_e32 v[16:17], 0
	v_mov_b64_e32 v[18:19], 0
	v_mov_b64_e32 v[28:29], 0
	v_mov_b64_e32 v[30:31], 0
	v_mov_b64_e32 v[32:33], 0
	v_mov_b64_e32 v[34:35], 0
	v_mov_b64_e32 v[44:45], 0
	v_mov_b64_e32 v[46:47], 0
	v_mov_b64_e32 v[48:49], 0
	v_mov_b64_e32 v[50:51], 0
	v_mov_b64_e32 v[60:61], 0
	v_mov_b64_e32 v[62:63], 0
	v_mov_b64_e32 v[64:65], 0
	v_mov_b64_e32 v[66:67], 0
	v_mov_b64_e32 v[68:69], 0
	v_mov_b64_e32 v[70:71], 0
	v_mov_b64_e32 v[72:73], 0
	v_mov_b64_e32 v[74:75], 0
	v_mov_b64_e32 v[84:85], 0
	v_mov_b64_e32 v[86:87], 0
	v_mov_b64_e32 v[88:89], 0
	v_mov_b64_e32 v[90:91], 0
	v_mov_b64_e32 v[100:101], 0
	v_mov_b64_e32 v[102:103], 0
	v_mov_b64_e32 v[104:105], 0
	v_mov_b64_e32 v[106:107], 0
	v_mov_b64_e32 v[116:117], 0
	v_mov_b64_e32 v[118:119], 0
	v_mov_b64_e32 v[120:121], 0
	v_mov_b64_e32 v[122:123], 0
	v_mov_b64_e32 v[76:77], 0
	v_mov_b64_e32 v[78:79], 0
	v_mov_b64_e32 v[80:81], 0
	v_mov_b64_e32 v[82:83], 0
	v_mov_b64_e32 v[92:93], 0
	v_mov_b64_e32 v[94:95], 0
	v_mov_b64_e32 v[96:97], 0
	v_mov_b64_e32 v[98:99], 0
	v_mov_b64_e32 v[108:109], 0
	v_mov_b64_e32 v[110:111], 0
	v_mov_b64_e32 v[112:113], 0
	v_mov_b64_e32 v[114:115], 0
	v_mov_b64_e32 v[124:125], 0
	v_mov_b64_e32 v[126:127], 0
	v_mov_b64_e32 v[128:129], 0
	v_mov_b64_e32 v[130:131], 0

.LBB0_369:
	s_ashr_i32 s35, s34, 31
	s_lshl_b64 s[6:7], s[34:35], 19
	s_add_u32 s38, s45, s6
	s_addc_u32 s39, s48, s7
	s_and_b64 s[6:7], s[4:5], exec
	s_cselect_b32 s1, s39, s9
	s_cselect_b32 s3, s38, s8
	s_ashr_i32 s41, s40, 31
	s_lshl_b64 s[6:7], s[40:41], 19
	s_add_u32 s18, s49, s6
	s_addc_u32 s19, s54, s7
	s_and_b64 s[6:7], s[4:5], exec
	s_cselect_b32 s12, s19, s11
	s_cselect_b32 s13, s18, s10
	s_add_u32 s6, s8, 0x40080
	s_addc_u32 s7, s9, 0
	s_add_u32 s14, s10, 0x100
	v_mov_b64_e32 v[4:5], 0
	s_addc_u32 s15, s11, 0
	s_mov_b32 s21, -2
	v_mov_b64_e32 v[6:7], 0
	v_mov_b64_e32 v[40:41], 0
	v_mov_b64_e32 v[42:43], 0
	v_mov_b64_e32 v[8:9], 0
	v_mov_b64_e32 v[10:11], 0
	v_mov_b64_e32 v[44:45], 0
	v_mov_b64_e32 v[46:47], 0
	v_mov_b64_e32 v[12:13], 0
	v_mov_b64_e32 v[14:15], 0
	v_mov_b64_e32 v[48:49], 0
	v_mov_b64_e32 v[50:51], 0
	v_mov_b64_e32 v[16:17], 0
	v_mov_b64_e32 v[18:19], 0
	v_mov_b64_e32 v[52:53], 0
	v_mov_b64_e32 v[54:55], 0
	v_mov_b64_e32 v[36:37], 0
	v_mov_b64_e32 v[38:39], 0
	v_mov_b64_e32 v[32:33], 0
	v_mov_b64_e32 v[34:35], 0
	v_mov_b64_e32 v[20:21], 0
	v_mov_b64_e32 v[22:23], 0
	v_mov_b64_e32 v[56:57], 0
	v_mov_b64_e32 v[58:59], 0
	v_mov_b64_e32 v[24:25], 0
	v_mov_b64_e32 v[26:27], 0
	v_mov_b64_e32 v[60:61], 0
	v_mov_b64_e32 v[62:63], 0
	v_mov_b64_e32 v[28:29], 0
	v_mov_b64_e32 v[30:31], 0
	v_mov_b64_e32 v[64:65], 0
	v_mov_b64_e32 v[66:67], 0
	s_waitcnt vmcnt(4)
	v_mov_b64_e32 v[68:69], 0
	v_mov_b64_e32 v[70:71], 0
	v_mov_b64_e32 v[116:117], 0
	v_mov_b64_e32 v[118:119], 0
	v_mov_b64_e32 v[72:73], 0
	v_mov_b64_e32 v[74:75], 0
	v_mov_b64_e32 v[120:121], 0
	v_mov_b64_e32 v[122:123], 0
	v_mov_b64_e32 v[76:77], 0
	v_mov_b64_e32 v[78:79], 0
	v_mov_b64_e32 v[124:125], 0
	v_mov_b64_e32 v[126:127], 0
	v_mov_b64_e32 v[80:81], 0
	v_mov_b64_e32 v[82:83], 0
	v_mov_b64_e32 v[128:129], 0
	v_mov_b64_e32 v[130:131], 0
	v_mov_b64_e32 v[112:113], 0
	v_mov_b64_e32 v[114:115], 0
	v_mov_b64_e32 v[108:109], 0
	v_mov_b64_e32 v[110:111], 0
	v_mov_b64_e32 v[84:85], 0
	v_mov_b64_e32 v[86:87], 0
	v_mov_b64_e32 v[132:133], 0
	v_mov_b64_e32 v[134:135], 0
	v_mov_b64_e32 v[88:89], 0
	v_mov_b64_e32 v[90:91], 0
	v_mov_b64_e32 v[136:137], 0
	v_mov_b64_e32 v[138:139], 0
	v_mov_b64_e32 v[92:93], 0
	v_mov_b64_e32 v[94:95], 0
	v_mov_b64_e32 v[140:141], 0
	v_mov_b64_e32 v[142:143], 0

.LBB0_769:
	s_add_u32 s6, s42, 0x80
	s_addc_u32 s7, s43, 0
	s_add_u32 s52, s52, 0x100
	v_mov_b64_e32 v[4:5], 0
	s_addc_u32 s53, s53, 0
	s_mov_b32 s42, 0
	v_mov_b64_e32 v[6:7], 0
	v_mov_b64_e32 v[8:9], 0
	v_mov_b64_e32 v[10:11], 0
	v_mov_b64_e32 v[20:21], 0
	v_mov_b64_e32 v[22:23], 0
	v_mov_b64_e32 v[24:25], 0
	v_mov_b64_e32 v[26:27], 0
	v_mov_b64_e32 v[36:37], 0
	v_mov_b64_e32 v[38:39], 0
	v_mov_b64_e32 v[40:41], 0
	v_mov_b64_e32 v[42:43], 0
	v_mov_b64_e32 v[52:53], 0
	v_mov_b64_e32 v[54:55], 0
	v_mov_b64_e32 v[56:57], 0
	v_mov_b64_e32 v[58:59], 0
	v_mov_b64_e32 v[12:13], 0
	v_mov_b64_e32 v[14:15], 0
	v_mov_b64_e32 v[16:17], 0
	v_mov_b64_e32 v[18:19], 0
	v_mov_b64_e32 v[28:29], 0
	v_mov_b64_e32 v[30:31], 0
	v_mov_b64_e32 v[32:33], 0
	v_mov_b64_e32 v[34:35], 0
	v_mov_b64_e32 v[44:45], 0
	v_mov_b64_e32 v[46:47], 0
	v_mov_b64_e32 v[48:49], 0
	v_mov_b64_e32 v[50:51], 0
	v_mov_b64_e32 v[60:61], 0
	v_mov_b64_e32 v[62:63], 0
	v_mov_b64_e32 v[64:65], 0
	v_mov_b64_e32 v[66:67], 0
	s_waitcnt vmcnt(4)
	v_mov_b64_e32 v[68:69], 0
	v_mov_b64_e32 v[70:71], 0
	v_mov_b64_e32 v[72:73], 0
	v_mov_b64_e32 v[74:75], 0
	v_mov_b64_e32 v[84:85], 0
	v_mov_b64_e32 v[86:87], 0
	v_mov_b64_e32 v[88:89], 0
	v_mov_b64_e32 v[90:91], 0
	v_mov_b64_e32 v[100:101], 0
	v_mov_b64_e32 v[102:103], 0
	v_mov_b64_e32 v[104:105], 0
	v_mov_b64_e32 v[106:107], 0
	v_mov_b64_e32 v[116:117], 0
	v_mov_b64_e32 v[118:119], 0
	v_mov_b64_e32 v[120:121], 0
	v_mov_b64_e32 v[122:123], 0
	v_mov_b64_e32 v[76:77], 0
	v_mov_b64_e32 v[78:79], 0
	v_mov_b64_e32 v[80:81], 0
	v_mov_b64_e32 v[82:83], 0
	v_mov_b64_e32 v[92:93], 0
	v_mov_b64_e32 v[94:95], 0
	v_mov_b64_e32 v[96:97], 0
	v_mov_b64_e32 v[98:99], 0
	v_mov_b64_e32 v[108:109], 0
	v_mov_b64_e32 v[110:111], 0
	v_mov_b64_e32 v[112:113], 0
	v_mov_b64_e32 v[114:115], 0
	v_mov_b64_e32 v[124:125], 0
	v_mov_b64_e32 v[126:127], 0
	v_mov_b64_e32 v[128:129], 0
	v_mov_b64_e32 v[130:131], 0

.LBB0_938:
	s_add_u32 s38, s38, 0x80
	s_addc_u32 s39, s39, 0
	s_add_u32 s31, s40, 0x100
	v_mov_b64_e32 v[4:5], 0
	s_addc_u32 s35, s41, 0
	s_mov_b32 s40, 0
	v_mov_b64_e32 v[6:7], 0
	v_mov_b64_e32 v[8:9], 0
	v_mov_b64_e32 v[10:11], 0
	v_mov_b64_e32 v[20:21], 0
	v_mov_b64_e32 v[22:23], 0
	v_mov_b64_e32 v[24:25], 0
	v_mov_b64_e32 v[26:27], 0
	v_mov_b64_e32 v[36:37], 0
	v_mov_b64_e32 v[38:39], 0
	v_mov_b64_e32 v[40:41], 0
	v_mov_b64_e32 v[42:43], 0
	v_mov_b64_e32 v[52:53], 0
	v_mov_b64_e32 v[54:55], 0
	v_mov_b64_e32 v[56:57], 0
	v_mov_b64_e32 v[58:59], 0
	v_mov_b64_e32 v[12:13], 0
	v_mov_b64_e32 v[14:15], 0
	v_mov_b64_e32 v[16:17], 0
	v_mov_b64_e32 v[18:19], 0
	v_mov_b64_e32 v[28:29], 0
	v_mov_b64_e32 v[30:31], 0
	v_mov_b64_e32 v[32:33], 0
	v_mov_b64_e32 v[34:35], 0
	v_mov_b64_e32 v[44:45], 0
	v_mov_b64_e32 v[46:47], 0
	v_mov_b64_e32 v[48:49], 0
	v_mov_b64_e32 v[50:51], 0
	v_mov_b64_e32 v[60:61], 0
	v_mov_b64_e32 v[62:63], 0
	v_mov_b64_e32 v[64:65], 0
	v_mov_b64_e32 v[66:67], 0
	v_mov_b64_e32 v[68:69], 0
	v_mov_b64_e32 v[70:71], 0
	v_mov_b64_e32 v[72:73], 0
	v_mov_b64_e32 v[74:75], 0
	v_mov_b64_e32 v[84:85], 0
	v_mov_b64_e32 v[86:87], 0
	v_mov_b64_e32 v[88:89], 0
	v_mov_b64_e32 v[90:91], 0
	v_mov_b64_e32 v[100:101], 0
	v_mov_b64_e32 v[102:103], 0
	v_mov_b64_e32 v[104:105], 0
	v_mov_b64_e32 v[106:107], 0
	v_mov_b64_e32 v[116:117], 0
	v_mov_b64_e32 v[118:119], 0
	v_mov_b64_e32 v[120:121], 0
	v_mov_b64_e32 v[122:123], 0
	v_mov_b64_e32 v[76:77], 0
	v_mov_b64_e32 v[78:79], 0
	v_mov_b64_e32 v[80:81], 0
	v_mov_b64_e32 v[82:83], 0
	v_mov_b64_e32 v[92:93], 0
	v_mov_b64_e32 v[94:95], 0
	v_mov_b64_e32 v[96:97], 0
	v_mov_b64_e32 v[98:99], 0
	v_mov_b64_e32 v[108:109], 0
	v_mov_b64_e32 v[110:111], 0
	v_mov_b64_e32 v[112:113], 0
	v_mov_b64_e32 v[114:115], 0
	v_mov_b64_e32 v[124:125], 0
	v_mov_b64_e32 v[126:127], 0
	v_mov_b64_e32 v[128:129], 0
	v_mov_b64_e32 v[130:131], 0
